# stack v80 + static s_setprio 1 for waves 0-3 (the other half than before) during the mixer phases and the branch GEMM
# baseline (speedup 1.0000x reference)
; #define LAS __attribute__((address_space(3)))
; __device__ __forceinline__ int opaque_bid() { int t = blockIdx.x; asm volatile("" : "+s"(t)); return t; }
; __device__ __forceinline__ int opaque_gd() { int t = gridDim.x; asm volatile("" : "+s"(t)); return t; }
; __device__ __forceinline__ int opaque_tid() { int t = threadIdx.x; asm volatile("" : "+v"(t)); return t; }
; __device__ __forceinline__ void bgemm_phase(LAS unsigned char* lds, const bf16_t* outs, const bf16_t* wbr, const bf16_t* zg, bf16_t* merged) {
;     using namespace pg8;
;     const int tid = opaque_tid(), wid = __builtin_amdgcn_readfirstlane(tid >> 6), lane = tid & 63, fr = lane & 15, fq = lane >> 4;
;     const int wm = wid >> 1, wn = wid & 1;
;     unsigned voff[2], voffB[2];
; #pragma unroll
;     for (int i = 0; i < 2; ++i) { int R, C; stage_rc(tid * 16 + i * 8192, R, C); voff[i] = (unsigned)(R * 256 + C) * 2u; voffB[i] = (unsigned)(((R & ~31) + perm32(R & 31)) * 256 + C) * 2u; }
;     const unsigned ldsw = (unsigned)wid * 1024u;
;     const int aoff = (wm >> 1) * HTB + lds_byte((wm & 1) * 64 + fr, fq * 8);
;     const int boff = 2 * HTB + lds_byte(wn * 64 + fr, fq * 8);
;     constexpr int STG = 3 * HTB;
;     ...
;     for (int u = opaque_bid(); u < 512; u += opaque_gd()) {
.LBB0_292:
	s_and_b64 vcc, exec, s[4:5]
	s_cbranch_vccz .LBB0_299
	v_mov_b32_e32 v0, s84
	s_waitcnt vmcnt(0)
	ds_read2_b64 v[4:7], v0 offset0:25 offset1:31
	ds_read2_b64 v[8:11], v0 offset0:29 offset1:30
	v_mov_b32_e32 v1, v202
	s_mov_b32 s0, s91
	v_mov_b32_e32 v203, 1
	v_mov_b32_e32 v210, 0xb00000
	v_mov_b32_e32 v212, 0x80
	v_mov_b32_e32 v254, 0xc0
	s_waitcnt lgkmcnt(0)
	v_readfirstlane_b32 s2, v4
	v_readfirstlane_b32 s8, v5
	v_readfirstlane_b32 s9, v8
	v_readfirstlane_b32 s12, v9
	v_readfirstlane_b32 s4, v10
	v_readfirstlane_b32 s5, v11
	v_readfirstlane_b32 s6, v6
	v_readfirstlane_b32 s7, v7
	s_cmpk_gt_i32 s0, 0x1ff
	v_readfirstlane_b32 s13, v1
	s_cbranch_scc1 .LBB0_298
	v_readlane_b32 s14, v255, 22
	v_readlane_b32 s15, v255, 23
	s_mov_b32 s16, s14
	s_ashr_i32 s17, s14, 31
	v_writelane_b32 v255, s14, 22
	v_and_b32_e32 v4, 15, v1
	v_bfe_u32 v5, v1, 4, 2
	v_writelane_b32 v255, s15, 23
	s_lshl_b64 s[14:15], s[16:17], 21
	s_add_u32 s2, s2, s14
	s_addc_u32 s23, s8, s15
	s_add_u32 s8, s9, 0x5800000
	s_addc_u32 s9, s12, 0
	s_ashr_i32 s14, s13, 7
	s_ashr_i32 s12, s13, 6
	s_lshl_b32 s13, s13, 6
	s_lshl_b32 s16, s14, 13
	v_lshlrev_b32_e32 v3, 2, v1
	s_and_b32 s13, s13, 0xffffc000
	v_lshlrev_b32_e32 v0, 6, v4
	v_lshlrev_b32_e32 v6, 4, v5
	s_and_b32 s16, s16, 0x2000
	v_and_b32_e32 v8, 32, v3
	s_and_b32 s15, s12, 1
	v_or_b32_e32 v7, v6, v0
	v_bitop3_b32 v0, v6, v8, v0 bitop3:0x36
	s_or_b32 s13, s16, s13
	v_or_b32_e32 v3, s13, v0
	s_lshl_b32 s13, s15, 13
	v_bitop3_b32 v145, v7, s13, v8 bitop3:0xde
	v_lshlrev_b32_e32 v7, 4, v1
	v_add_u32_e32 v0, 0x2000, v7
	v_ashrrev_i32_e32 v8, 31, v0
	v_lshrrev_b32_e32 v8, 22, v8
	v_add_u32_e32 v8, v0, v8
	v_ashrrev_i32_e32 v8, 10, v8
	v_mul_i32_i24_e32 v9, 0x400, v8
	v_sub_u32_e32 v0, v0, v9
	v_lshrrev_b32_e32 v9, 4, v0
	v_bitop3_b32 v0, v9, v0, 32 bitop3:0x6c
	v_ashrrev_i32_e32 v9, 31, v0
	v_lshrrev_b32_e32 v9, 26, v9
	v_add_u32_e32 v9, v0, v9
	v_ashrrev_i32_e32 v10, 6, v9
	v_and_b32_e32 v9, 0xc0, v9
	v_sub_u32_e32 v0, v0, v9
	v_mov_b32_e32 v23, 1
	v_lshlrev_b32_e32 v11, 3, v8
	v_lshlrev_b32_e32 v17, 5, v8
	v_ashrrev_i16_sdwa v0, v23, sext(v0) dst_sel:DWORD dst_unused:UNUSED_PAD src0_sel:DWORD src1_sel:BYTE_0
	v_and_b32_e32 v11, -16, v11
	v_and_b32_e32 v17, 32, v17
	v_bfe_i32 v9, v0, 0, 16
	v_add_u32_e32 v11, v10, v11
	v_add_lshl_u32 v17, v17, v9, 1
	v_and_b32_e32 v12, 0x7fffe0, v11
	v_lshrrev_b32_e32 v15, 2, v11
	v_lshlrev_b32_e32 v16, 1, v11
	v_lshl_add_u32 v100, v11, 9, v17
	v_bfe_i32 v11, v1, 27, 1
	v_and_b32_e32 v13, 3, v10
	v_lshrrev_b32_e32 v11, 22, v11
	v_or_b32_e32 v14, v12, v13
	v_and_b32_e32 v15, 4, v15
	v_and_b32_e32 v16, 24, v16
	v_add_u32_e32 v11, v7, v11
	v_or3_b32 v14, v14, v15, v16
	v_and_b32_e32 v11, 0xfffffc00, v11
	v_lshl_add_u32 v0, v14, 9, v17
	v_sub_u32_e32 v7, v7, v11
	v_ashrrev_i32_e32 v14, 31, v1
	v_lshrrev_b32_e32 v11, 4, v7
	v_lshrrev_b32_e32 v14, 26, v14
	v_bitop3_b32 v11, v11, v7, 32 bitop3:0x6c
	v_ashrrev_i32_e32 v7, 31, v7
	v_add_u32_e32 v14, v1, v14
	v_lshrrev_b32_e32 v7, 26, v7
	v_ashrrev_i32_e32 v1, 6, v14
	v_add_u32_e32 v7, v11, v7
	v_lshlrev_b32_e32 v17, 3, v1
	v_ashrrev_i32_e32 v7, 6, v7
	v_and_b32_e32 v17, -16, v17
	v_add_u32_e32 v17, v7, v17
	v_and_b32_e32 v19, 3, v7
	v_mul_i32_i24_e32 v7, 64, v7
	s_lshl_b32 s12, s12, 10
	v_sub_u32_e32 v7, v11, v7
	v_and_b32_e32 v18, 0x7fffe0, v17
	v_lshrrev_b32_e32 v21, 2, v17
	v_lshlrev_b32_e32 v22, 1, v17
	v_lshlrev_b32_e32 v1, 5, v1
	v_ashrrev_i16_sdwa v7, v23, sext(v7) dst_sel:DWORD dst_unused:UNUSED_PAD src0_sel:DWORD src1_sel:BYTE_0
	s_add_i32 s30, s12, 0
	s_lshl_b32 s12, s14, 10
	s_lshl_b32 s13, s15, 7
	v_or_b32_e32 v20, v18, v19
	v_and_b32_e32 v21, 4, v21
	v_and_b32_e32 v22, 24, v22
	v_and_b32_e32 v1, 32, v1
	v_bfe_i32 v7, v7, 0, 16
	s_or_b32 s12, s13, s12
	v_lshl_or_b32 v215, s14, 6, v4
	v_or3_b32 v20, v20, v21, v22
	v_add_lshl_u32 v1, v1, v7, 1
	v_or3_b32 v4, s12, v6, v4
	v_lshl_add_u32 v102, v20, 9, v1
	v_lshl_add_u32 v104, v17, 9, v1
	v_lshlrev_b32_e32 v1, 3, v5
	v_ashrrev_i32_e32 v5, 31, v4
	v_lshlrev_b64 v[106:107], 3, v[4:5]
	v_or_b32_e32 v4, v12, v16
	v_lshlrev_b32_e32 v5, 6, v8
	v_or3_b32 v4, v4, v15, v13
	v_and_b32_e32 v5, 64, v5
	v_lshl_or_b32 v4, v4, 9, v5
	v_lshlrev_b32_e32 v6, 1, v9
	v_add_u32_e32 v108, v4, v6
	v_or_b32_e32 v4, v18, v22
	v_or3_b32 v4, v4, v21, v19
	v_and_b32_e32 v9, 64, v14
	v_lshl_or_b32 v4, v4, 9, v9
	v_lshl_add_u32 v110, v7, 1, v4
	v_lshlrev_b32_e32 v4, 12, v8
	v_and_b32_e32 v4, 0xffffe000, v4
	v_lshl_add_u32 v4, v10, 9, v4
	v_or_b32_e32 v4, v4, v5
	v_mov_b32_e32 v105, v2
	v_add_u32_e32 v4, v4, v6
	v_mov_b32_e32 v5, v2
	v_or_b32_e32 v214, 0x8000, v145
	v_mov_b32_e32 v203, 1
	v_lshl_or_b32 v216, s15, 6, v1
	v_mov_b32_e32 v101, v2
	v_mov_b32_e32 v103, v2
	v_mov_b32_e32 v1, v2
	s_add_i32 s31, s30, 0x18000
	s_add_i32 s34, s30, 0x1a000
	v_mov_b32_e32 v109, v2
	v_mov_b32_e32 v111, v2
	v_lshl_add_u64 v[112:113], s[6:7], 0, v[4:5]
	v_lshl_add_u64 v[114:115], s[6:7], 0, v[104:105]
	v_readfirstlane_b32 s98, v202
	s_cmp_lt_u32 s98, 0x100
	s_cbranch_scc0 .Lsprio_bg
	s_setprio 1

; __device__ __forceinline__ int opaque_bid() { int t = blockIdx.x; asm volatile("" : "+s"(t)); return t; }
; __device__ __forceinline__ int opaque_gd() { int t = gridDim.x; asm volatile("" : "+s"(t)); return t; }
; __device__ __forceinline__ Params fetchP(const LAS Params* lp0) { unsigned la = (unsigned)(unsigned long long)lp0; asm volatile("" : "+v"(la)); const LAS Params* lp = (const LAS Params*)la; Params q; PFIELDS(PFETCH) q.ph_lo = 0; q.ph_hi = 0; return q; }
; __device__ __forceinline__ void run_phase(const LAS Params* lp, int ph, LAS unsigned char* lds) {
;     ...
;     case 2: for (int it = opaque_bid(); it < 1280; it += opaque_gd()) { const Params p = fetchP(lp); const int jx = (it & ~255) + (it & 7) * 32 + ((it & 255) >> 3);
;             if (it < 256) hgrn_item(p, l, jx, 1, lds); else if (it < 768) gmlp_item(p, l, jx - 256, lds); else lru_fix_item(p, l, jx - 768); } break;
.LBB0_300:
	s_and_b64 vcc, exec, s[4:5]
	s_cbranch_vccz .LBB0_430
	s_cmp_gt_i32 s88, 0
	s_mov_b64 s[4:5], -1
	s_cbranch_scc0 .LBB0_428
	s_cmp_gt_i32 s88, 1
	s_cbranch_scc0 .LBB0_348
	s_mov_b32 s72, s91
	s_cmpk_gt_i32 s72, 0x4ff
	s_cbranch_scc1 .LBB0_347
	v_readlane_b32 s4, v255, 22
	v_readlane_b32 s5, v255, 23
	s_mov_b32 s0, s4
	s_ashr_i32 s5, s4, 31
	v_writelane_b32 v255, s0, 22
	s_lshl_b32 s28, s4, 8
	s_lshl_b64 s[26:27], s[4:5], 9
	v_writelane_b32 v255, s1, 23
	s_ashr_i32 s29, s28, 31
	v_readfirstlane_b32 s98, v202
	s_cmp_lt_u32 s98, 0x100
	s_cbranch_scc0 .Lsprio_m2
	s_setprio 1

; __device__ __forceinline__ int opaque_bid() { int t = blockIdx.x; asm volatile("" : "+s"(t)); return t; }
; __device__ __forceinline__ int opaque_gd() { int t = gridDim.x; asm volatile("" : "+s"(t)); return t; }
; __device__ __forceinline__ Params fetchP(const LAS Params* lp0) { unsigned la = (unsigned)(unsigned long long)lp0; asm volatile("" : "+v"(la)); const LAS Params* lp = (const LAS Params*)la; Params q; PFIELDS(PFETCH) q.ph_lo = 0; q.ph_hi = 0; return q; }
; __device__ __forceinline__ void run_phase(const LAS Params* lp, int ph, LAS unsigned char* lds) {
;     ...
;     case 1: for (int it = opaque_bid(); it < 1280; it += opaque_gd()) { const Params p = fetchP(lp); const int jx = (it & ~255) + (it & 7) * 32 + ((it & 255) >> 3);
;             if (it < 256) hgrn_item(p, l, jx, 0, lds); else if (it < 768) attn_item(p, l, jx - 256, lds); else lru_item(p, l, jx - 768, lds); } break;
.LBB0_348:
	s_andn2_b64 vcc, exec, s[4:5]
	s_cbranch_vccnz .LBB0_427
	s_mov_b32 s2, s91
	s_cmpk_gt_i32 s2, 0x4ff
	s_cbranch_scc1 .LBB0_427
	v_readlane_b32 s4, v255, 22
	v_readlane_b32 s5, v255, 23
	s_mov_b32 s0, s4
	s_ashr_i32 s5, s4, 31
	v_writelane_b32 v255, s0, 22
	s_lshl_b64 s[12:13], s[4:5], 8
	s_lshl_b32 s40, s4, 8
	s_lshl_b32 s87, s4, 10
	v_writelane_b32 v255, s1, 23
	s_lshl_b64 s[4:5], s[4:5], 2
	v_writelane_b32 v255, s4, 14
	s_mov_b32 s68, s94
	s_mov_b32 s43, s97
	v_writelane_b32 v255, s5, 15
	v_readfirstlane_b32 s98, v202
	s_cmp_lt_u32 s98, 0x100
	s_cbranch_scc0 .Lsprio_m1
	s_setprio 1
